# v33 + packed add in SwiGLU epilogue + write-through (sc1) final LayerNorm output stores
# speedup vs baseline: 1.0007x; 1.0007x over previous
.LBB0_312:
	s_lshl_b32 s12, s72, 12
	s_and_b32 s12, s12, 0x1000
	s_add_i32 s12, s12, 0x20000
	v_lshl_add_u32 v194, s7, 8, v1
	s_lshl_b32 s7, s68, 2
	s_add_i32 s7, s12, s7
	v_lshl_add_u32 v54, v163, 2, s7
	v_add_u32_e32 v189, s12, v186
	ds_read_b128 v[146:149], v54 offset:2048
	ds_read_b128 v[150:153], v54 offset:2064
	ds_read_b128 v[174:177], v54 offset:2560
	ds_read_b128 v[178:181], v54 offset:2576
	ds_read_b128 v[182:185], v54 offset:3072
	ds_read_b128 v[66:69], v54 offset:3088
	ds_read_b128 v[70:73], v54 offset:3584
	ds_read_b128 v[50:53], v54 offset:3600
	ds_read_b64 v[56:57], v189
	v_mov_b64_e32 v[190:191], s[10:11]
	v_lshl_or_b32 v195, s6, 7, v187
	s_mov_b32 s12, 0xbfb8aa3b
	v_mad_i64_i32 v[190:191], vcc, v194, s83, v[190:191]
	v_lshlrev_b32_e32 v195, 1, v195
	ds_read_b64 v[192:193], v189 offset:128
	v_add_co_u32_e32 v190, vcc, v190, v195
	s_nop 1
	v_addc_co_u32_e32 v191, vcc, 0, v191, vcc
	s_waitcnt lgkmcnt(1)
	v_pk_fma_f32 v[142:143], v[146:147], v[56:57], v[142:143] op_sel_hi:[1,0,1] neg_lo:[1,0,0] neg_hi:[1,0,0]
	v_pk_fma_f32 v[144:145], v[148:149], v[56:57], v[144:145] op_sel_hi:[1,0,1] neg_lo:[1,0,0] neg_hi:[1,0,0]
	v_pk_fma_f32 v[134:135], v[150:151], v[56:57], v[134:135] op_sel_hi:[1,0,1] neg_lo:[1,0,0] neg_hi:[1,0,0]
	v_pk_fma_f32 v[136:137], v[152:153], v[56:57], v[136:137] op_sel_hi:[1,0,1] neg_lo:[1,0,0] neg_hi:[1,0,0]
	v_pk_fma_f32 v[138:139], v[174:175], v[56:57], v[138:139] op_sel_hi:[1,0,1] neg_lo:[1,0,0] neg_hi:[1,0,0]
	v_pk_fma_f32 v[140:141], v[176:177], v[56:57], v[140:141] op_sel_hi:[1,0,1] neg_lo:[1,0,0] neg_hi:[1,0,0]
	v_pk_fma_f32 v[130:131], v[178:179], v[56:57], v[130:131] op_sel_hi:[1,0,1] neg_lo:[1,0,0] neg_hi:[1,0,0]
	v_pk_fma_f32 v[132:133], v[180:181], v[56:57], v[132:133] op_sel_hi:[1,0,1] neg_lo:[1,0,0] neg_hi:[1,0,0]
	v_pk_fma_f32 v[142:143], v[56:57], v[142:143], v[182:183] op_sel:[1,0,0]
	v_pk_fma_f32 v[144:145], v[56:57], v[144:145], v[184:185] op_sel:[1,0,0]
	v_pk_fma_f32 v[134:135], v[56:57], v[134:135], v[66:67] op_sel:[1,0,0]
	v_pk_fma_f32 v[136:137], v[56:57], v[136:137], v[68:69] op_sel:[1,0,0]
	v_pk_fma_f32 v[138:139], v[56:57], v[138:139], v[70:71] op_sel:[1,0,0]
	v_pk_fma_f32 v[140:141], v[56:57], v[140:141], v[72:73] op_sel:[1,0,0]
	v_pk_fma_f32 v[130:131], v[56:57], v[130:131], v[50:51] op_sel:[1,0,0]
	v_pk_fma_f32 v[132:133], v[56:57], v[132:133], v[52:53] op_sel:[1,0,0]
	ds_read_b64 v[56:57], v189 offset:256
	v_pk_mul_f32 v[194:195], v[142:143], s[12:13] op_sel_hi:[1,0]
	v_pk_mul_f32 v[196:197], v[144:145], s[12:13] op_sel_hi:[1,0]
	v_pk_mul_f32 v[198:199], v[134:135], s[12:13] op_sel_hi:[1,0]
	v_pk_mul_f32 v[200:201], v[136:137], s[12:13] op_sel_hi:[1,0]
	v_pk_mul_f32 v[142:143], v[142:143], v[138:139]
	v_pk_mul_f32 v[144:145], v[144:145], v[140:141]
	v_pk_mul_f32 v[134:135], v[134:135], v[130:131]
	v_pk_mul_f32 v[136:137], v[136:137], v[132:133]
	v_exp_f32_e32 v194, v194
	v_exp_f32_e32 v195, v195
	v_exp_f32_e32 v196, v196
	v_exp_f32_e32 v197, v197
	v_exp_f32_e32 v198, v198
	v_exp_f32_e32 v199, v199
	v_exp_f32_e32 v200, v200
	v_exp_f32_e32 v201, v201
	v_pk_add_f32 v[194:195], v[194:195], 1.0 op_sel_hi:[1,0]
	v_pk_add_f32 v[196:197], v[196:197], 1.0 op_sel_hi:[1,0]
	v_pk_add_f32 v[198:199], v[198:199], 1.0 op_sel_hi:[1,0]
	v_pk_add_f32 v[200:201], v[200:201], 1.0 op_sel_hi:[1,0]
	v_rcp_f32_e32 v194, v194
	v_rcp_f32_e32 v195, v195
	v_rcp_f32_e32 v196, v196
	v_rcp_f32_e32 v197, v197
	v_rcp_f32_e32 v198, v198
	v_rcp_f32_e32 v199, v199
	v_rcp_f32_e32 v200, v200
	v_rcp_f32_e32 v201, v201
	v_pk_mul_f32 v[142:143], v[142:143], v[194:195]
	v_pk_mul_f32 v[144:145], v[144:145], v[196:197]
	v_pk_mul_f32 v[134:135], v[134:135], v[198:199]
	v_pk_mul_f32 v[136:137], v[136:137], v[200:201]
	v_cvt_pk_bf16_f32 v138, v142, v143
	v_cvt_pk_bf16_f32 v139, v144, v145
	v_cvt_pk_bf16_f32 v140, v134, v135
	v_cvt_pk_bf16_f32 v141, v136, v137
	global_store_dwordx4 v[190:191], v[138:141], off
	v_add_co_u32_e32 v190, vcc, 0x16000, v190
	s_nop 1
	v_addc_co_u32_e32 v191, vcc, 0, v191, vcc
	s_waitcnt lgkmcnt(1)
	v_pk_fma_f32 v[126:127], v[146:147], v[192:193], v[126:127] op_sel_hi:[1,0,1] neg_lo:[1,0,0] neg_hi:[1,0,0]
	v_pk_fma_f32 v[128:129], v[148:149], v[192:193], v[128:129] op_sel_hi:[1,0,1] neg_lo:[1,0,0] neg_hi:[1,0,0]
	v_pk_fma_f32 v[118:119], v[150:151], v[192:193], v[118:119] op_sel_hi:[1,0,1] neg_lo:[1,0,0] neg_hi:[1,0,0]
	v_pk_fma_f32 v[120:121], v[152:153], v[192:193], v[120:121] op_sel_hi:[1,0,1] neg_lo:[1,0,0] neg_hi:[1,0,0]
	v_pk_fma_f32 v[122:123], v[174:175], v[192:193], v[122:123] op_sel_hi:[1,0,1] neg_lo:[1,0,0] neg_hi:[1,0,0]
	v_pk_fma_f32 v[124:125], v[176:177], v[192:193], v[124:125] op_sel_hi:[1,0,1] neg_lo:[1,0,0] neg_hi:[1,0,0]
	v_pk_fma_f32 v[114:115], v[178:179], v[192:193], v[114:115] op_sel_hi:[1,0,1] neg_lo:[1,0,0] neg_hi:[1,0,0]
	v_pk_fma_f32 v[116:117], v[180:181], v[192:193], v[116:117] op_sel_hi:[1,0,1] neg_lo:[1,0,0] neg_hi:[1,0,0]
	v_pk_fma_f32 v[126:127], v[192:193], v[126:127], v[182:183] op_sel:[1,0,0]
	v_pk_fma_f32 v[128:129], v[192:193], v[128:129], v[184:185] op_sel:[1,0,0]
	v_pk_fma_f32 v[118:119], v[192:193], v[118:119], v[66:67] op_sel:[1,0,0]
	v_pk_fma_f32 v[120:121], v[192:193], v[120:121], v[68:69] op_sel:[1,0,0]
	v_pk_fma_f32 v[122:123], v[192:193], v[122:123], v[70:71] op_sel:[1,0,0]
	v_pk_fma_f32 v[124:125], v[192:193], v[124:125], v[72:73] op_sel:[1,0,0]
	v_pk_fma_f32 v[114:115], v[192:193], v[114:115], v[50:51] op_sel:[1,0,0]
	v_pk_fma_f32 v[116:117], v[192:193], v[116:117], v[52:53] op_sel:[1,0,0]
	ds_read_b64 v[192:193], v189 offset:384
	v_pk_mul_f32 v[194:195], v[126:127], s[12:13] op_sel_hi:[1,0]
	v_pk_mul_f32 v[196:197], v[128:129], s[12:13] op_sel_hi:[1,0]
	v_pk_mul_f32 v[198:199], v[118:119], s[12:13] op_sel_hi:[1,0]
	v_pk_mul_f32 v[200:201], v[120:121], s[12:13] op_sel_hi:[1,0]
	v_pk_mul_f32 v[126:127], v[126:127], v[122:123]
	v_pk_mul_f32 v[128:129], v[128:129], v[124:125]
	v_pk_mul_f32 v[118:119], v[118:119], v[114:115]
	v_pk_mul_f32 v[120:121], v[120:121], v[116:117]
	v_exp_f32_e32 v194, v194
	v_exp_f32_e32 v195, v195
	v_exp_f32_e32 v196, v196
	v_exp_f32_e32 v197, v197
	v_exp_f32_e32 v198, v198
	v_exp_f32_e32 v199, v199
	v_exp_f32_e32 v200, v200
	v_exp_f32_e32 v201, v201
	v_pk_add_f32 v[194:195], v[194:195], 1.0 op_sel_hi:[1,0]
	v_pk_add_f32 v[196:197], v[196:197], 1.0 op_sel_hi:[1,0]
	v_pk_add_f32 v[198:199], v[198:199], 1.0 op_sel_hi:[1,0]
	v_pk_add_f32 v[200:201], v[200:201], 1.0 op_sel_hi:[1,0]
	v_rcp_f32_e32 v194, v194
	v_rcp_f32_e32 v195, v195
	v_rcp_f32_e32 v196, v196
	v_rcp_f32_e32 v197, v197
	v_rcp_f32_e32 v198, v198
	v_rcp_f32_e32 v199, v199
	v_rcp_f32_e32 v200, v200
	v_rcp_f32_e32 v201, v201
	v_pk_mul_f32 v[126:127], v[126:127], v[194:195]
	v_pk_mul_f32 v[128:129], v[128:129], v[196:197]
	v_pk_mul_f32 v[118:119], v[118:119], v[198:199]
	v_pk_mul_f32 v[120:121], v[120:121], v[200:201]
	v_cvt_pk_bf16_f32 v122, v126, v127
	v_cvt_pk_bf16_f32 v123, v128, v129
	v_cvt_pk_bf16_f32 v124, v118, v119
	v_cvt_pk_bf16_f32 v125, v120, v121
	global_store_dwordx4 v[190:191], v[122:125], off
	v_add_co_u32_e32 v190, vcc, 0x16000, v190
	s_nop 1
	v_addc_co_u32_e32 v191, vcc, 0, v191, vcc
	s_waitcnt lgkmcnt(1)
	v_pk_fma_f32 v[110:111], v[146:147], v[56:57], v[110:111] op_sel_hi:[1,0,1] neg_lo:[1,0,0] neg_hi:[1,0,0]
	v_pk_fma_f32 v[112:113], v[148:149], v[56:57], v[112:113] op_sel_hi:[1,0,1] neg_lo:[1,0,0] neg_hi:[1,0,0]
	v_pk_fma_f32 v[102:103], v[150:151], v[56:57], v[102:103] op_sel_hi:[1,0,1] neg_lo:[1,0,0] neg_hi:[1,0,0]
	v_pk_fma_f32 v[104:105], v[152:153], v[56:57], v[104:105] op_sel_hi:[1,0,1] neg_lo:[1,0,0] neg_hi:[1,0,0]
	v_pk_fma_f32 v[106:107], v[174:175], v[56:57], v[106:107] op_sel_hi:[1,0,1] neg_lo:[1,0,0] neg_hi:[1,0,0]
	v_pk_fma_f32 v[108:109], v[176:177], v[56:57], v[108:109] op_sel_hi:[1,0,1] neg_lo:[1,0,0] neg_hi:[1,0,0]
	v_pk_fma_f32 v[98:99], v[178:179], v[56:57], v[98:99] op_sel_hi:[1,0,1] neg_lo:[1,0,0] neg_hi:[1,0,0]
	v_pk_fma_f32 v[100:101], v[180:181], v[56:57], v[100:101] op_sel_hi:[1,0,1] neg_lo:[1,0,0] neg_hi:[1,0,0]
	v_pk_fma_f32 v[110:111], v[56:57], v[110:111], v[182:183] op_sel:[1,0,0]
	v_pk_fma_f32 v[112:113], v[56:57], v[112:113], v[184:185] op_sel:[1,0,0]
	v_pk_fma_f32 v[102:103], v[56:57], v[102:103], v[66:67] op_sel:[1,0,0]
	v_pk_fma_f32 v[104:105], v[56:57], v[104:105], v[68:69] op_sel:[1,0,0]
	v_pk_fma_f32 v[106:107], v[56:57], v[106:107], v[70:71] op_sel:[1,0,0]
	v_pk_fma_f32 v[108:109], v[56:57], v[108:109], v[72:73] op_sel:[1,0,0]
	v_pk_fma_f32 v[98:99], v[56:57], v[98:99], v[50:51] op_sel:[1,0,0]
	v_pk_fma_f32 v[100:101], v[56:57], v[100:101], v[52:53] op_sel:[1,0,0]
	ds_read_b64 v[56:57], v189 offset:1024
	v_pk_mul_f32 v[194:195], v[110:111], s[12:13] op_sel_hi:[1,0]
	v_pk_mul_f32 v[196:197], v[112:113], s[12:13] op_sel_hi:[1,0]
	v_pk_mul_f32 v[198:199], v[102:103], s[12:13] op_sel_hi:[1,0]
	v_pk_mul_f32 v[200:201], v[104:105], s[12:13] op_sel_hi:[1,0]
	v_pk_mul_f32 v[110:111], v[110:111], v[106:107]
	v_pk_mul_f32 v[112:113], v[112:113], v[108:109]
	v_pk_mul_f32 v[102:103], v[102:103], v[98:99]
	v_pk_mul_f32 v[104:105], v[104:105], v[100:101]
	v_exp_f32_e32 v194, v194
	v_exp_f32_e32 v195, v195
	v_exp_f32_e32 v196, v196
	v_exp_f32_e32 v197, v197
	v_exp_f32_e32 v198, v198
	v_exp_f32_e32 v199, v199
	v_exp_f32_e32 v200, v200
	v_exp_f32_e32 v201, v201
	v_pk_add_f32 v[194:195], v[194:195], 1.0 op_sel_hi:[1,0]
	v_pk_add_f32 v[196:197], v[196:197], 1.0 op_sel_hi:[1,0]
	v_pk_add_f32 v[198:199], v[198:199], 1.0 op_sel_hi:[1,0]
	v_pk_add_f32 v[200:201], v[200:201], 1.0 op_sel_hi:[1,0]
	v_rcp_f32_e32 v194, v194
	v_rcp_f32_e32 v195, v195
	v_rcp_f32_e32 v196, v196
	v_rcp_f32_e32 v197, v197
	v_rcp_f32_e32 v198, v198
	v_rcp_f32_e32 v199, v199
	v_rcp_f32_e32 v200, v200
	v_rcp_f32_e32 v201, v201
	v_pk_mul_f32 v[110:111], v[110:111], v[194:195]
	v_pk_mul_f32 v[112:113], v[112:113], v[196:197]
	v_pk_mul_f32 v[102:103], v[102:103], v[198:199]
	v_pk_mul_f32 v[104:105], v[104:105], v[200:201]
	v_cvt_pk_bf16_f32 v106, v110, v111
	v_cvt_pk_bf16_f32 v107, v112, v113
	v_cvt_pk_bf16_f32 v108, v102, v103
	v_cvt_pk_bf16_f32 v109, v104, v105
	global_store_dwordx4 v[190:191], v[106:109], off
	v_add_co_u32_e32 v190, vcc, 0x16000, v190
	s_nop 1
	v_addc_co_u32_e32 v191, vcc, 0, v191, vcc
	s_waitcnt lgkmcnt(1)
	v_pk_fma_f32 v[94:95], v[146:147], v[192:193], v[94:95] op_sel_hi:[1,0,1] neg_lo:[1,0,0] neg_hi:[1,0,0]
	v_pk_fma_f32 v[96:97], v[148:149], v[192:193], v[96:97] op_sel_hi:[1,0,1] neg_lo:[1,0,0] neg_hi:[1,0,0]
	v_pk_fma_f32 v[86:87], v[150:151], v[192:193], v[86:87] op_sel_hi:[1,0,1] neg_lo:[1,0,0] neg_hi:[1,0,0]
	v_pk_fma_f32 v[88:89], v[152:153], v[192:193], v[88:89] op_sel_hi:[1,0,1] neg_lo:[1,0,0] neg_hi:[1,0,0]
	v_pk_fma_f32 v[90:91], v[174:175], v[192:193], v[90:91] op_sel_hi:[1,0,1] neg_lo:[1,0,0] neg_hi:[1,0,0]
	v_pk_fma_f32 v[92:93], v[176:177], v[192:193], v[92:93] op_sel_hi:[1,0,1] neg_lo:[1,0,0] neg_hi:[1,0,0]
	v_pk_fma_f32 v[82:83], v[178:179], v[192:193], v[82:83] op_sel_hi:[1,0,1] neg_lo:[1,0,0] neg_hi:[1,0,0]
	v_pk_fma_f32 v[84:85], v[180:181], v[192:193], v[84:85] op_sel_hi:[1,0,1] neg_lo:[1,0,0] neg_hi:[1,0,0]
	v_pk_fma_f32 v[94:95], v[192:193], v[94:95], v[182:183] op_sel:[1,0,0]
	v_pk_fma_f32 v[96:97], v[192:193], v[96:97], v[184:185] op_sel:[1,0,0]
	v_pk_fma_f32 v[86:87], v[192:193], v[86:87], v[66:67] op_sel:[1,0,0]
	v_pk_fma_f32 v[88:89], v[192:193], v[88:89], v[68:69] op_sel:[1,0,0]
	v_pk_fma_f32 v[90:91], v[192:193], v[90:91], v[70:71] op_sel:[1,0,0]
	v_pk_fma_f32 v[92:93], v[192:193], v[92:93], v[72:73] op_sel:[1,0,0]
	v_pk_fma_f32 v[82:83], v[192:193], v[82:83], v[50:51] op_sel:[1,0,0]
	v_pk_fma_f32 v[84:85], v[192:193], v[84:85], v[52:53] op_sel:[1,0,0]
	ds_read_b64 v[192:193], v189 offset:1152
	v_pk_mul_f32 v[194:195], v[94:95], s[12:13] op_sel_hi:[1,0]
	v_pk_mul_f32 v[196:197], v[96:97], s[12:13] op_sel_hi:[1,0]
	v_pk_mul_f32 v[198:199], v[86:87], s[12:13] op_sel_hi:[1,0]
	v_pk_mul_f32 v[200:201], v[88:89], s[12:13] op_sel_hi:[1,0]
	v_pk_mul_f32 v[94:95], v[94:95], v[90:91]
	v_pk_mul_f32 v[96:97], v[96:97], v[92:93]
	v_pk_mul_f32 v[86:87], v[86:87], v[82:83]
	v_pk_mul_f32 v[88:89], v[88:89], v[84:85]
	v_exp_f32_e32 v194, v194
	v_exp_f32_e32 v195, v195
	v_exp_f32_e32 v196, v196
	v_exp_f32_e32 v197, v197
	v_exp_f32_e32 v198, v198
	v_exp_f32_e32 v199, v199
	v_exp_f32_e32 v200, v200
	v_exp_f32_e32 v201, v201
	v_pk_add_f32 v[194:195], v[194:195], 1.0 op_sel_hi:[1,0]
	v_pk_add_f32 v[196:197], v[196:197], 1.0 op_sel_hi:[1,0]
	v_pk_add_f32 v[198:199], v[198:199], 1.0 op_sel_hi:[1,0]
	v_pk_add_f32 v[200:201], v[200:201], 1.0 op_sel_hi:[1,0]
	v_rcp_f32_e32 v194, v194
	v_rcp_f32_e32 v195, v195
	v_rcp_f32_e32 v196, v196
	v_rcp_f32_e32 v197, v197
	v_rcp_f32_e32 v198, v198
	v_rcp_f32_e32 v199, v199
	v_rcp_f32_e32 v200, v200
	v_rcp_f32_e32 v201, v201
	v_pk_mul_f32 v[94:95], v[94:95], v[194:195]
	v_pk_mul_f32 v[96:97], v[96:97], v[196:197]
	v_pk_mul_f32 v[86:87], v[86:87], v[198:199]
	v_pk_mul_f32 v[88:89], v[88:89], v[200:201]
	v_cvt_pk_bf16_f32 v90, v94, v95
	v_cvt_pk_bf16_f32 v91, v96, v97
	v_cvt_pk_bf16_f32 v92, v86, v87
	v_cvt_pk_bf16_f32 v93, v88, v89
	global_store_dwordx4 v[190:191], v[90:93], off
	v_add_co_u32_e32 v190, vcc, 0x6e000, v190
	s_nop 1
	v_addc_co_u32_e32 v191, vcc, 0, v191, vcc
	s_waitcnt lgkmcnt(1)
	v_pk_fma_f32 v[78:79], v[146:147], v[56:57], v[78:79] op_sel_hi:[1,0,1] neg_lo:[1,0,0] neg_hi:[1,0,0]
	v_pk_fma_f32 v[80:81], v[148:149], v[56:57], v[80:81] op_sel_hi:[1,0,1] neg_lo:[1,0,0] neg_hi:[1,0,0]
	v_pk_fma_f32 v[62:63], v[150:151], v[56:57], v[62:63] op_sel_hi:[1,0,1] neg_lo:[1,0,0] neg_hi:[1,0,0]
	v_pk_fma_f32 v[64:65], v[152:153], v[56:57], v[64:65] op_sel_hi:[1,0,1] neg_lo:[1,0,0] neg_hi:[1,0,0]
	v_pk_fma_f32 v[74:75], v[174:175], v[56:57], v[74:75] op_sel_hi:[1,0,1] neg_lo:[1,0,0] neg_hi:[1,0,0]
	v_pk_fma_f32 v[76:77], v[176:177], v[56:57], v[76:77] op_sel_hi:[1,0,1] neg_lo:[1,0,0] neg_hi:[1,0,0]
	v_pk_fma_f32 v[58:59], v[178:179], v[56:57], v[58:59] op_sel_hi:[1,0,1] neg_lo:[1,0,0] neg_hi:[1,0,0]
	v_pk_fma_f32 v[60:61], v[180:181], v[56:57], v[60:61] op_sel_hi:[1,0,1] neg_lo:[1,0,0] neg_hi:[1,0,0]
	v_pk_fma_f32 v[78:79], v[56:57], v[78:79], v[182:183] op_sel:[1,0,0]
	v_pk_fma_f32 v[80:81], v[56:57], v[80:81], v[184:185] op_sel:[1,0,0]
	v_pk_fma_f32 v[62:63], v[56:57], v[62:63], v[66:67] op_sel:[1,0,0]
	v_pk_fma_f32 v[64:65], v[56:57], v[64:65], v[68:69] op_sel:[1,0,0]
	v_pk_fma_f32 v[74:75], v[56:57], v[74:75], v[70:71] op_sel:[1,0,0]
	v_pk_fma_f32 v[76:77], v[56:57], v[76:77], v[72:73] op_sel:[1,0,0]
	v_pk_fma_f32 v[58:59], v[56:57], v[58:59], v[50:51] op_sel:[1,0,0]
	v_pk_fma_f32 v[60:61], v[56:57], v[60:61], v[52:53] op_sel:[1,0,0]
	ds_read_b64 v[56:57], v189 offset:1280
	v_pk_mul_f32 v[194:195], v[78:79], s[12:13] op_sel_hi:[1,0]
	v_pk_mul_f32 v[196:197], v[80:81], s[12:13] op_sel_hi:[1,0]
	v_pk_mul_f32 v[198:199], v[62:63], s[12:13] op_sel_hi:[1,0]
	v_pk_mul_f32 v[200:201], v[64:65], s[12:13] op_sel_hi:[1,0]
	v_pk_mul_f32 v[78:79], v[78:79], v[74:75]
	v_pk_mul_f32 v[80:81], v[80:81], v[76:77]
	v_pk_mul_f32 v[62:63], v[62:63], v[58:59]
	v_pk_mul_f32 v[64:65], v[64:65], v[60:61]
	v_exp_f32_e32 v194, v194
	v_exp_f32_e32 v195, v195
	v_exp_f32_e32 v196, v196
	v_exp_f32_e32 v197, v197
	v_exp_f32_e32 v198, v198
	v_exp_f32_e32 v199, v199
	v_exp_f32_e32 v200, v200
	v_exp_f32_e32 v201, v201
	v_pk_add_f32 v[194:195], v[194:195], 1.0 op_sel_hi:[1,0]
	v_pk_add_f32 v[196:197], v[196:197], 1.0 op_sel_hi:[1,0]
	v_pk_add_f32 v[198:199], v[198:199], 1.0 op_sel_hi:[1,0]
	v_pk_add_f32 v[200:201], v[200:201], 1.0 op_sel_hi:[1,0]
	v_rcp_f32_e32 v194, v194
	v_rcp_f32_e32 v195, v195
	v_rcp_f32_e32 v196, v196
	v_rcp_f32_e32 v197, v197
	v_rcp_f32_e32 v198, v198
	v_rcp_f32_e32 v199, v199
	v_rcp_f32_e32 v200, v200
	v_rcp_f32_e32 v201, v201
	v_pk_mul_f32 v[78:79], v[78:79], v[194:195]
	v_pk_mul_f32 v[80:81], v[80:81], v[196:197]
	v_pk_mul_f32 v[62:63], v[62:63], v[198:199]
	v_pk_mul_f32 v[64:65], v[64:65], v[200:201]
	v_cvt_pk_bf16_f32 v74, v78, v79
	v_cvt_pk_bf16_f32 v75, v80, v81
	v_cvt_pk_bf16_f32 v76, v62, v63
	v_cvt_pk_bf16_f32 v77, v64, v65
	global_store_dwordx4 v[190:191], v[74:77], off
	v_add_co_u32_e32 v190, vcc, 0x16000, v190
	s_nop 1
	v_addc_co_u32_e32 v191, vcc, 0, v191, vcc
	s_waitcnt lgkmcnt(1)
	v_pk_fma_f32 v[46:47], v[146:147], v[192:193], v[46:47] op_sel_hi:[1,0,1] neg_lo:[1,0,0] neg_hi:[1,0,0]
	v_pk_fma_f32 v[48:49], v[148:149], v[192:193], v[48:49] op_sel_hi:[1,0,1] neg_lo:[1,0,0] neg_hi:[1,0,0]
	v_pk_fma_f32 v[38:39], v[150:151], v[192:193], v[38:39] op_sel_hi:[1,0,1] neg_lo:[1,0,0] neg_hi:[1,0,0]
	v_pk_fma_f32 v[40:41], v[152:153], v[192:193], v[40:41] op_sel_hi:[1,0,1] neg_lo:[1,0,0] neg_hi:[1,0,0]
	v_pk_fma_f32 v[42:43], v[174:175], v[192:193], v[42:43] op_sel_hi:[1,0,1] neg_lo:[1,0,0] neg_hi:[1,0,0]
	v_pk_fma_f32 v[44:45], v[176:177], v[192:193], v[44:45] op_sel_hi:[1,0,1] neg_lo:[1,0,0] neg_hi:[1,0,0]
	v_pk_fma_f32 v[34:35], v[178:179], v[192:193], v[34:35] op_sel_hi:[1,0,1] neg_lo:[1,0,0] neg_hi:[1,0,0]
	v_pk_fma_f32 v[36:37], v[180:181], v[192:193], v[36:37] op_sel_hi:[1,0,1] neg_lo:[1,0,0] neg_hi:[1,0,0]
	v_pk_fma_f32 v[46:47], v[192:193], v[46:47], v[182:183] op_sel:[1,0,0]
	v_pk_fma_f32 v[48:49], v[192:193], v[48:49], v[184:185] op_sel:[1,0,0]
	v_pk_fma_f32 v[38:39], v[192:193], v[38:39], v[66:67] op_sel:[1,0,0]
	v_pk_fma_f32 v[40:41], v[192:193], v[40:41], v[68:69] op_sel:[1,0,0]
	v_pk_fma_f32 v[42:43], v[192:193], v[42:43], v[70:71] op_sel:[1,0,0]
	v_pk_fma_f32 v[44:45], v[192:193], v[44:45], v[72:73] op_sel:[1,0,0]
	v_pk_fma_f32 v[34:35], v[192:193], v[34:35], v[50:51] op_sel:[1,0,0]
	v_pk_fma_f32 v[36:37], v[192:193], v[36:37], v[52:53] op_sel:[1,0,0]
	ds_read_b64 v[192:193], v189 offset:1408
	v_pk_mul_f32 v[194:195], v[46:47], s[12:13] op_sel_hi:[1,0]
	v_pk_mul_f32 v[196:197], v[48:49], s[12:13] op_sel_hi:[1,0]
	v_pk_mul_f32 v[198:199], v[38:39], s[12:13] op_sel_hi:[1,0]
	v_pk_mul_f32 v[200:201], v[40:41], s[12:13] op_sel_hi:[1,0]
	v_pk_mul_f32 v[46:47], v[46:47], v[42:43]
	v_pk_mul_f32 v[48:49], v[48:49], v[44:45]
	v_pk_mul_f32 v[38:39], v[38:39], v[34:35]
	v_pk_mul_f32 v[40:41], v[40:41], v[36:37]
	v_exp_f32_e32 v194, v194
	v_exp_f32_e32 v195, v195
	v_exp_f32_e32 v196, v196
	v_exp_f32_e32 v197, v197
	v_exp_f32_e32 v198, v198
	v_exp_f32_e32 v199, v199
	v_exp_f32_e32 v200, v200
	v_exp_f32_e32 v201, v201
	v_pk_add_f32 v[194:195], v[194:195], 1.0 op_sel_hi:[1,0]
	v_pk_add_f32 v[196:197], v[196:197], 1.0 op_sel_hi:[1,0]
	v_pk_add_f32 v[198:199], v[198:199], 1.0 op_sel_hi:[1,0]
	v_pk_add_f32 v[200:201], v[200:201], 1.0 op_sel_hi:[1,0]
	v_rcp_f32_e32 v194, v194
	v_rcp_f32_e32 v195, v195
	v_rcp_f32_e32 v196, v196
	v_rcp_f32_e32 v197, v197
	v_rcp_f32_e32 v198, v198
	v_rcp_f32_e32 v199, v199
	v_rcp_f32_e32 v200, v200
	v_rcp_f32_e32 v201, v201
	v_pk_mul_f32 v[46:47], v[46:47], v[194:195]
	v_pk_mul_f32 v[48:49], v[48:49], v[196:197]
	v_pk_mul_f32 v[38:39], v[38:39], v[198:199]
	v_pk_mul_f32 v[40:41], v[40:41], v[200:201]
	v_cvt_pk_bf16_f32 v42, v46, v47
	v_cvt_pk_bf16_f32 v43, v48, v49
	v_cvt_pk_bf16_f32 v44, v38, v39
	v_cvt_pk_bf16_f32 v45, v40, v41
	global_store_dwordx4 v[190:191], v[42:45], off
	v_add_co_u32_e32 v190, vcc, 0x16000, v190
	s_nop 1
	v_addc_co_u32_e32 v191, vcc, 0, v191, vcc
	s_waitcnt lgkmcnt(1)
	v_pk_fma_f32 v[30:31], v[146:147], v[56:57], v[30:31] op_sel_hi:[1,0,1] neg_lo:[1,0,0] neg_hi:[1,0,0]
	v_pk_fma_f32 v[32:33], v[148:149], v[56:57], v[32:33] op_sel_hi:[1,0,1] neg_lo:[1,0,0] neg_hi:[1,0,0]
	v_pk_fma_f32 v[22:23], v[150:151], v[56:57], v[22:23] op_sel_hi:[1,0,1] neg_lo:[1,0,0] neg_hi:[1,0,0]
	v_pk_fma_f32 v[24:25], v[152:153], v[56:57], v[24:25] op_sel_hi:[1,0,1] neg_lo:[1,0,0] neg_hi:[1,0,0]
	v_pk_fma_f32 v[26:27], v[174:175], v[56:57], v[26:27] op_sel_hi:[1,0,1] neg_lo:[1,0,0] neg_hi:[1,0,0]
	v_pk_fma_f32 v[28:29], v[176:177], v[56:57], v[28:29] op_sel_hi:[1,0,1] neg_lo:[1,0,0] neg_hi:[1,0,0]
	v_pk_fma_f32 v[18:19], v[178:179], v[56:57], v[18:19] op_sel_hi:[1,0,1] neg_lo:[1,0,0] neg_hi:[1,0,0]
	v_pk_fma_f32 v[20:21], v[180:181], v[56:57], v[20:21] op_sel_hi:[1,0,1] neg_lo:[1,0,0] neg_hi:[1,0,0]
	v_pk_fma_f32 v[30:31], v[56:57], v[30:31], v[182:183] op_sel:[1,0,0]
	v_pk_fma_f32 v[32:33], v[56:57], v[32:33], v[184:185] op_sel:[1,0,0]
	v_pk_fma_f32 v[22:23], v[56:57], v[22:23], v[66:67] op_sel:[1,0,0]
	v_pk_fma_f32 v[24:25], v[56:57], v[24:25], v[68:69] op_sel:[1,0,0]
	v_pk_fma_f32 v[26:27], v[56:57], v[26:27], v[70:71] op_sel:[1,0,0]
	v_pk_fma_f32 v[28:29], v[56:57], v[28:29], v[72:73] op_sel:[1,0,0]
	v_pk_fma_f32 v[18:19], v[56:57], v[18:19], v[50:51] op_sel:[1,0,0]
	v_pk_fma_f32 v[20:21], v[56:57], v[20:21], v[52:53] op_sel:[1,0,0]
	v_pk_mul_f32 v[194:195], v[30:31], s[12:13] op_sel_hi:[1,0]
	v_pk_mul_f32 v[196:197], v[32:33], s[12:13] op_sel_hi:[1,0]
	v_pk_mul_f32 v[198:199], v[22:23], s[12:13] op_sel_hi:[1,0]
	v_pk_mul_f32 v[200:201], v[24:25], s[12:13] op_sel_hi:[1,0]
	v_pk_mul_f32 v[30:31], v[30:31], v[26:27]
	v_pk_mul_f32 v[32:33], v[32:33], v[28:29]
	v_pk_mul_f32 v[22:23], v[22:23], v[18:19]
	v_pk_mul_f32 v[24:25], v[24:25], v[20:21]
	v_exp_f32_e32 v194, v194
	v_exp_f32_e32 v195, v195
	v_exp_f32_e32 v196, v196
	v_exp_f32_e32 v197, v197
	v_exp_f32_e32 v198, v198
	v_exp_f32_e32 v199, v199
	v_exp_f32_e32 v200, v200
	v_exp_f32_e32 v201, v201
	v_pk_add_f32 v[194:195], v[194:195], 1.0 op_sel_hi:[1,0]
	v_pk_add_f32 v[196:197], v[196:197], 1.0 op_sel_hi:[1,0]
	v_pk_add_f32 v[198:199], v[198:199], 1.0 op_sel_hi:[1,0]
	v_pk_add_f32 v[200:201], v[200:201], 1.0 op_sel_hi:[1,0]
	v_rcp_f32_e32 v194, v194
	v_rcp_f32_e32 v195, v195
	v_rcp_f32_e32 v196, v196
	v_rcp_f32_e32 v197, v197
	v_rcp_f32_e32 v198, v198
	v_rcp_f32_e32 v199, v199
	v_rcp_f32_e32 v200, v200
	v_rcp_f32_e32 v201, v201
	v_pk_mul_f32 v[30:31], v[30:31], v[194:195]
	v_pk_mul_f32 v[32:33], v[32:33], v[196:197]
	v_pk_mul_f32 v[22:23], v[22:23], v[198:199]
	v_pk_mul_f32 v[24:25], v[24:25], v[200:201]
	v_cvt_pk_bf16_f32 v26, v30, v31
	v_cvt_pk_bf16_f32 v27, v32, v33
	v_cvt_pk_bf16_f32 v28, v22, v23
	v_cvt_pk_bf16_f32 v29, v24, v25
	global_store_dwordx4 v[190:191], v[26:29], off
	v_add_co_u32_e32 v190, vcc, 0x16000, v190
	s_nop 1
	v_addc_co_u32_e32 v191, vcc, 0, v191, vcc
	s_waitcnt lgkmcnt(0)
	v_pk_fma_f32 v[14:15], v[146:147], v[192:193], v[14:15] op_sel_hi:[1,0,1] neg_lo:[1,0,0] neg_hi:[1,0,0]
	v_pk_fma_f32 v[16:17], v[148:149], v[192:193], v[16:17] op_sel_hi:[1,0,1] neg_lo:[1,0,0] neg_hi:[1,0,0]
	v_pk_fma_f32 v[6:7], v[150:151], v[192:193], v[6:7] op_sel_hi:[1,0,1] neg_lo:[1,0,0] neg_hi:[1,0,0]
	v_pk_fma_f32 v[8:9], v[152:153], v[192:193], v[8:9] op_sel_hi:[1,0,1] neg_lo:[1,0,0] neg_hi:[1,0,0]
	v_pk_fma_f32 v[10:11], v[174:175], v[192:193], v[10:11] op_sel_hi:[1,0,1] neg_lo:[1,0,0] neg_hi:[1,0,0]
	v_pk_fma_f32 v[12:13], v[176:177], v[192:193], v[12:13] op_sel_hi:[1,0,1] neg_lo:[1,0,0] neg_hi:[1,0,0]
	v_pk_fma_f32 v[2:3], v[178:179], v[192:193], v[2:3] op_sel_hi:[1,0,1] neg_lo:[1,0,0] neg_hi:[1,0,0]
	v_pk_fma_f32 v[4:5], v[180:181], v[192:193], v[4:5] op_sel_hi:[1,0,1] neg_lo:[1,0,0] neg_hi:[1,0,0]
	v_pk_fma_f32 v[14:15], v[192:193], v[14:15], v[182:183] op_sel:[1,0,0]
	v_pk_fma_f32 v[16:17], v[192:193], v[16:17], v[184:185] op_sel:[1,0,0]
	v_pk_fma_f32 v[6:7], v[192:193], v[6:7], v[66:67] op_sel:[1,0,0]
	v_pk_fma_f32 v[8:9], v[192:193], v[8:9], v[68:69] op_sel:[1,0,0]
	v_pk_fma_f32 v[10:11], v[192:193], v[10:11], v[70:71] op_sel:[1,0,0]
	v_pk_fma_f32 v[12:13], v[192:193], v[12:13], v[72:73] op_sel:[1,0,0]
	v_pk_fma_f32 v[2:3], v[192:193], v[2:3], v[50:51] op_sel:[1,0,0]
	v_pk_fma_f32 v[4:5], v[192:193], v[4:5], v[52:53] op_sel:[1,0,0]
	v_pk_mul_f32 v[194:195], v[14:15], s[12:13] op_sel_hi:[1,0]
	v_pk_mul_f32 v[196:197], v[16:17], s[12:13] op_sel_hi:[1,0]
	v_pk_mul_f32 v[198:199], v[6:7], s[12:13] op_sel_hi:[1,0]
	v_pk_mul_f32 v[200:201], v[8:9], s[12:13] op_sel_hi:[1,0]
	v_pk_mul_f32 v[14:15], v[14:15], v[10:11]
	v_pk_mul_f32 v[16:17], v[16:17], v[12:13]
	v_pk_mul_f32 v[6:7], v[6:7], v[2:3]
	v_pk_mul_f32 v[8:9], v[8:9], v[4:5]
	v_exp_f32_e32 v194, v194
	v_exp_f32_e32 v195, v195
	v_exp_f32_e32 v196, v196
	v_exp_f32_e32 v197, v197
	v_exp_f32_e32 v198, v198
	v_exp_f32_e32 v199, v199
	v_exp_f32_e32 v200, v200
	v_exp_f32_e32 v201, v201
	v_pk_add_f32 v[194:195], v[194:195], 1.0 op_sel_hi:[1,0]
	v_pk_add_f32 v[196:197], v[196:197], 1.0 op_sel_hi:[1,0]
	v_pk_add_f32 v[198:199], v[198:199], 1.0 op_sel_hi:[1,0]
	v_pk_add_f32 v[200:201], v[200:201], 1.0 op_sel_hi:[1,0]
	v_rcp_f32_e32 v194, v194
	v_rcp_f32_e32 v195, v195
	v_rcp_f32_e32 v196, v196
	v_rcp_f32_e32 v197, v197
	v_rcp_f32_e32 v198, v198
	v_rcp_f32_e32 v199, v199
	v_rcp_f32_e32 v200, v200
	v_rcp_f32_e32 v201, v201
	v_pk_mul_f32 v[14:15], v[14:15], v[194:195]
	v_pk_mul_f32 v[16:17], v[16:17], v[196:197]
	v_pk_mul_f32 v[6:7], v[6:7], v[198:199]
	v_pk_mul_f32 v[8:9], v[8:9], v[200:201]
	v_cvt_pk_bf16_f32 v10, v14, v15
	v_cvt_pk_bf16_f32 v11, v16, v17
	v_cvt_pk_bf16_f32 v12, v6, v7
	v_cvt_pk_bf16_f32 v13, v8, v9
	global_store_dwordx4 v[190:191], v[10:13], off
	s_mov_b64 s[56:57], -1
	s_andn2_b64 vcc, exec, s[38:39]
	s_cbranch_vccnz .LBB0_299
	s_andn2_b64 vcc, exec, s[40:41]
	s_cbranch_vccnz .LBB0_298
	s_barrier
	s_branch .LBB0_298

.LBB0_1109:
	s_add_i32 s2, s0, s86
	s_cmp_lt_i32 s2, 0x8200
	s_cselect_b32 s4, s2, s0
	s_ashr_i32 s5, s4, 31
	s_lshl_b64 s[14:15], s[4:5], 11
	s_add_i32 s8, s18, s0
	s_cmp_lt_i32 s8, 0x8200
	s_cselect_b64 s[10:11], -1, 0
	s_and_b64 s[4:5], s[10:11], exec
	s_cselect_b32 s4, s8, s0
	s_ashr_i32 s5, s4, 31
	s_lshl_b64 s[16:17], s[4:5], 11
	s_add_i32 s4, s19, s0
	s_cmp_lt_i32 s4, 0x8200
	s_cselect_b64 s[6:7], -1, 0
	s_and_b64 s[12:13], s[6:7], exec
	s_cselect_b32 s12, s4, s0
	s_ashr_i32 s1, s0, 31
	s_lshl_b64 s[22:23], s[0:1], 11
	s_waitcnt vmcnt(4)
	v_lshl_add_u64 v[36:37], v[32:33], 0, s[22:23]
	global_load_dwordx2 v[38:39], v[36:37], off
	global_load_dwordx2 v[40:41], v[36:37], off offset:512
	global_load_dwordx2 v[42:43], v[36:37], off offset:1024
	global_load_dwordx2 v[44:45], v[36:37], off offset:1536
	s_ashr_i32 s13, s12, 31
	s_lshl_b64 s[12:13], s[12:13], 11
	v_lshl_add_u64 v[88:89], v[32:33], 0, s[12:13]
	s_lshl_b64 s[0:1], s[0:1], 12
	v_lshl_add_u64 v[90:91], v[34:35], 0, s[0:1]
	s_cmp_gt_i32 s2, 0x81ff
	s_waitcnt vmcnt(3)
	v_lshlrev_b32_e32 v53, 16, v39
	v_lshlrev_b32_e32 v52, 16, v38
	v_and_b32_e32 v37, 0xffff0000, v39
	v_and_b32_e32 v36, 0xffff0000, v38
	s_waitcnt vmcnt(2)
	v_lshlrev_b32_e32 v59, 16, v41
	v_lshlrev_b32_e32 v58, 16, v40
	v_and_b32_e32 v39, 0xffff0000, v41
	v_and_b32_e32 v38, 0xffff0000, v40
	s_waitcnt vmcnt(1)
	v_lshlrev_b32_e32 v62, 16, v42
	v_and_b32_e32 v63, 0xffff0000, v42
	v_lshlrev_b32_e32 v64, 16, v43
	v_and_b32_e32 v65, 0xffff0000, v43
	v_pk_add_f32 v[40:41], v[52:53], v[36:37]
	v_pk_add_f32 v[42:43], v[58:59], v[38:39]
	s_waitcnt vmcnt(0)
	v_lshlrev_b32_e32 v66, 16, v44
	v_and_b32_e32 v82, 0xffff0000, v44
	v_add_f32_e32 v44, v40, v41
	v_pk_add_f32 v[70:71], v[42:43], v[42:43] op_sel_hi:[0,1]
	v_and_b32_e32 v72, 0xffff0000, v45
	v_add_f32_e32 v67, v62, v63
	v_add_f32_e32 v83, v64, v65
	v_add_f32_e32 v73, 0, v44
	v_lshlrev_b32_e32 v70, 16, v45
	v_pk_add_f32 v[40:41], v[66:67], v[82:83]
	v_pk_add_f32 v[42:43], v[70:71], v[72:73]
	s_nop 0
	v_pk_add_f32 v[40:41], v[40:41], v[42:43]
	s_nop 0
	v_add_f32_e32 v40, v40, v41
	ds_bpermute_b32 v41, v74, v40
	s_waitcnt lgkmcnt(0)
	v_add_f32_e32 v40, v40, v41
	ds_bpermute_b32 v41, v75, v40
	s_waitcnt lgkmcnt(0)
	v_add_f32_e32 v40, v40, v41
	ds_bpermute_b32 v41, v76, v40
	s_waitcnt lgkmcnt(0)
	v_add_f32_e32 v40, v40, v41
	ds_bpermute_b32 v41, v77, v40
	s_waitcnt lgkmcnt(0)
	v_add_f32_e32 v42, v40, v41
	ds_bpermute_b32 v43, v78, v42
	v_lshl_add_u64 v[40:41], v[32:33], 0, s[14:15]
	global_load_dwordx2 v[68:69], v[40:41], off
	global_load_dwordx2 v[60:61], v[40:41], off offset:512
	global_load_dwordx2 v[56:57], v[40:41], off offset:1024
	global_load_dwordx2 v[54:55], v[40:41], off offset:1536
	v_lshl_add_u64 v[40:41], v[32:33], 0, s[16:17]
	s_waitcnt lgkmcnt(0)
	v_add_f32_e32 v42, v42, v43
	ds_bpermute_b32 v43, v79, v42
	s_waitcnt lgkmcnt(0)
	v_add_f32_e32 v42, v42, v43
	v_fmac_f32_e32 v36, 0xba800000, v42
	v_fmac_f32_e32 v37, 0xba800000, v42
	v_fmac_f32_e32 v53, 0xba800000, v42
	v_fmac_f32_e32 v38, 0xba800000, v42
	v_fmac_f32_e32 v39, 0xba800000, v42
	v_fmac_f32_e32 v59, 0xba800000, v42
	v_fmac_f32_e32 v52, 0xba800000, v42
	v_fmac_f32_e32 v58, 0xba800000, v42
	v_fmac_f32_e32 v62, 0xba800000, v42
	v_fmac_f32_e32 v64, 0xba800000, v42
	v_mov_b32_e32 v84, v53
	v_mov_b32_e32 v85, v37
	v_mov_b32_e32 v53, v36
	v_mov_b32_e32 v86, v59
	v_mov_b32_e32 v87, v39
	v_mov_b32_e32 v59, v38
	v_fmac_f32_e32 v63, 0xba800000, v42
	v_fmac_f32_e32 v65, 0xba800000, v42
	v_fmac_f32_e32 v72, 0xba800000, v42
	v_fmac_f32_e32 v70, 0xba800000, v42
	v_fmac_f32_e32 v82, 0xba800000, v42
	v_fmac_f32_e32 v66, 0xba800000, v42
	v_mul_f32_e32 v36, v62, v62
	v_mul_f32_e32 v38, v64, v64
	v_pk_mul_f32 v[42:43], v[84:85], v[84:85]
	v_pk_mul_f32 v[44:45], v[52:53], v[52:53]
	v_pk_mul_f32 v[46:47], v[86:87], v[86:87]
	v_pk_mul_f32 v[48:49], v[58:59], v[58:59]
	v_pk_fma_f32 v[36:37], v[62:63], v[62:63], v[36:37] op_sel_hi:[1,1,0]
	v_pk_fma_f32 v[38:39], v[64:65], v[64:65], v[38:39] op_sel_hi:[1,1,0]
	v_pk_mov_b32 v[50:51], v[44:45], v[42:43] op_sel:[1,0]
	v_mov_b32_e32 v45, v43
	v_pk_mov_b32 v[42:43], v[48:49], v[46:47] op_sel:[1,0]
	v_mov_b32_e32 v49, v47
	v_mul_f32_e32 v36, v66, v66
	v_mul_f32_e32 v38, v82, v82
	v_pk_add_f32 v[44:45], v[50:51], v[44:45]
	v_pk_add_f32 v[42:43], v[42:43], v[48:49]
	v_pk_add_f32 v[36:37], v[36:37], v[38:39]
	v_pk_add_f32 v[38:39], v[44:45], v[44:45] op_sel_hi:[0,1]
	v_pk_add_f32 v[42:43], v[42:43], v[42:43] op_sel_hi:[0,1]
	v_mul_f32_e32 v38, v70, v70
	v_mul_f32_e32 v42, v72, v72
	v_pk_add_f32 v[38:39], v[38:39], v[42:43]
	global_load_dwordx2 v[50:51], v[40:41], off
	global_load_dwordx2 v[48:49], v[40:41], off offset:512
	global_load_dwordx2 v[46:47], v[40:41], off offset:1024
	global_load_dwordx2 v[44:45], v[40:41], off offset:1536
	v_pk_add_f32 v[36:37], v[36:37], v[38:39]
	s_nop 0
	v_add_f32_e32 v36, v36, v37
	ds_bpermute_b32 v37, v74, v36
	s_waitcnt lgkmcnt(0)
	v_add_f32_e32 v67, v36, v37
	global_load_dwordx2 v[42:43], v[88:89], off
	global_load_dwordx2 v[40:41], v[88:89], off offset:512
	global_load_dwordx2 v[38:39], v[88:89], off offset:1024
	global_load_dwordx2 v[36:37], v[88:89], off offset:1536
	ds_bpermute_b32 v71, v75, v67
	s_waitcnt lgkmcnt(0)
	v_add_f32_e32 v67, v67, v71
	ds_bpermute_b32 v71, v76, v67
	s_waitcnt lgkmcnt(0)
	v_add_f32_e32 v67, v67, v71
	ds_bpermute_b32 v71, v77, v67
	s_waitcnt lgkmcnt(0)
	v_add_f32_e32 v67, v67, v71
	ds_bpermute_b32 v71, v78, v67
	s_waitcnt lgkmcnt(0)
	v_add_f32_e32 v67, v67, v71
	ds_bpermute_b32 v71, v79, v67
	s_waitcnt lgkmcnt(0)
	v_add_f32_e32 v67, v67, v71
	v_fmamk_f32 v67, v67, 0x3a800000, v80
	v_mul_f32_e32 v71, 0x4f800000, v67
	v_cmp_gt_f32_e32 vcc, s20, v67
	s_nop 1
	v_cndmask_b32_e32 v71, v67, v71, vcc
	v_sqrt_f32_e32 v73, v71
	v_mov_b32_e32 v67, v82
	v_add_u32_e32 v82, -1, v73
	v_add_u32_e32 v83, 1, v73
	v_fma_f32 v88, -v82, v73, v71
	v_fma_f32 v89, -v83, v73, v71
	v_cmp_ge_f32_e64 s[0:1], 0, v88
	s_nop 1
	v_cndmask_b32_e64 v73, v73, v82, s[0:1]
	v_cmp_lt_f32_e64 s[0:1], 0, v89
	s_nop 1
	v_cndmask_b32_e64 v73, v73, v83, s[0:1]
	v_mul_f32_e32 v82, 0x37800000, v73
	v_cndmask_b32_e32 v73, v73, v82, vcc
	v_cmp_class_f32_e32 vcc, v71, v81
	s_nop 1
	v_cndmask_b32_e32 v73, v73, v71, vcc
	v_div_scale_f32 v82, s[0:1], v73, v73, 1.0
	v_rcp_f32_e32 v83, v82
	v_mov_b32_e32 v71, v72
	v_div_scale_f32 v72, vcc, 1.0, v73, 1.0
	v_fma_f32 v88, -v82, v83, 1.0
	v_fmac_f32_e32 v83, v88, v83
	v_mul_f32_e32 v88, v72, v83
	v_fma_f32 v89, -v82, v88, v72
	v_fmac_f32_e32 v88, v89, v83
	v_fma_f32 v72, -v82, v88, v72
	v_div_fmas_f32 v72, v72, v83, v88
	v_div_fixup_f32 v72, v72, v73, 1.0
	v_pk_mul_f32 v[52:53], v[52:53], v[72:73] op_sel_hi:[1,0]
	v_pk_mul_f32 v[82:83], v[84:85], v[72:73] op_sel_hi:[1,0]
	v_pk_mul_f32 v[58:59], v[58:59], v[72:73] op_sel_hi:[1,0]
	v_pk_mul_f32 v[84:85], v[86:87], v[72:73] op_sel_hi:[1,0]
	v_pk_mul_f32 v[86:87], v[62:63], v[72:73] op_sel_hi:[1,0]
	v_pk_mul_f32 v[88:89], v[64:65], v[72:73] op_sel_hi:[1,0]
	v_pk_mul_f32 v[66:67], v[66:67], v[72:73] op_sel_hi:[1,0]
	v_pk_mul_f32 v[92:93], v[70:71], v[72:73] op_sel_hi:[1,0]
	v_pk_fma_f32 v[64:65], v[2:3], v[82:83], v[6:7]
	v_pk_fma_f32 v[62:63], v[0:1], v[52:53], v[4:5]
	v_pk_fma_f32 v[72:73], v[10:11], v[84:85], v[18:19]
	v_pk_fma_f32 v[70:71], v[8:9], v[58:59], v[16:17]
	v_pk_fma_f32 v[84:85], v[14:15], v[88:89], v[22:23]
	v_pk_fma_f32 v[82:83], v[12:13], v[86:87], v[20:21]
	v_pk_fma_f32 v[88:89], v[26:27], v[92:93], v[30:31]
	v_pk_fma_f32 v[86:87], v[24:25], v[66:67], v[28:29]
	global_store_dwordx4 v[90:91], v[62:65], off sc1
	global_store_dwordx4 v[90:91], v[70:73], off offset:1024 sc1
	global_store_dwordx4 v[90:91], v[82:85], off offset:2048 sc1
	global_store_dwordx4 v[90:91], v[86:89], off offset:3072 sc1
	s_cbranch_scc1 .LBB0_1112
	s_waitcnt vmcnt(15)
	v_lshlrev_b32_e32 v53, 16, v69
	v_lshlrev_b32_e32 v52, 16, v68
	v_and_b32_e32 v59, 0xffff0000, v69
	v_and_b32_e32 v58, 0xffff0000, v68
	s_waitcnt vmcnt(14)
	v_lshlrev_b32_e32 v65, 16, v61
	v_lshlrev_b32_e32 v64, 16, v60
	v_and_b32_e32 v61, 0xffff0000, v61
	v_and_b32_e32 v60, 0xffff0000, v60
	v_pk_add_f32 v[62:63], v[52:53], v[58:59]
	v_pk_add_f32 v[66:67], v[64:65], v[60:61]
	v_add_f32_e32 v62, v62, v63
	s_waitcnt vmcnt(13)
	v_lshlrev_b32_e32 v68, 16, v56
	v_and_b32_e32 v69, 0xffff0000, v56
	v_lshlrev_b32_e32 v56, 16, v57
	v_and_b32_e32 v57, 0xffff0000, v57
	s_waitcnt vmcnt(12)
	v_lshlrev_b32_e32 v63, 16, v54
	v_and_b32_e32 v83, 0xffff0000, v54
	v_lshlrev_b32_e32 v71, 16, v55
	v_and_b32_e32 v73, 0xffff0000, v55
	v_pk_add_f32 v[54:55], v[66:67], v[66:67] op_sel:[0,1] op_sel_hi:[1,0]
	v_add_f32_e32 v62, 0, v62
	v_add_f32_e32 v70, v68, v69
	v_add_f32_e32 v72, v56, v57
	v_mov_b32_e32 v55, v83
	v_pk_add_f32 v[54:55], v[62:63], v[54:55]
	v_pk_add_f32 v[66:67], v[70:71], v[72:73]
	s_ashr_i32 s3, s2, 31
	v_pk_add_f32 v[54:55], v[54:55], v[66:67]
	s_nop 0
	v_add_f32_e32 v54, v54, v55
	ds_bpermute_b32 v55, v74, v54
	s_waitcnt lgkmcnt(0)
	v_add_f32_e32 v54, v54, v55
	ds_bpermute_b32 v55, v75, v54
	s_waitcnt lgkmcnt(0)
	v_add_f32_e32 v54, v54, v55
	ds_bpermute_b32 v55, v76, v54
	s_waitcnt lgkmcnt(0)
	v_add_f32_e32 v54, v54, v55
	ds_bpermute_b32 v55, v77, v54
	s_waitcnt lgkmcnt(0)
	v_add_f32_e32 v54, v54, v55
	ds_bpermute_b32 v55, v78, v54
	s_waitcnt lgkmcnt(0)
	v_add_f32_e32 v54, v54, v55
	ds_bpermute_b32 v55, v79, v54
	s_waitcnt lgkmcnt(0)
	v_add_f32_e32 v62, v54, v55
	v_fmac_f32_e32 v58, 0xba800000, v62
	v_fmac_f32_e32 v59, 0xba800000, v62
	v_fmac_f32_e32 v53, 0xba800000, v62
	v_fmac_f32_e32 v52, 0xba800000, v62
	v_mov_b32_e32 v54, v53
	v_mov_b32_e32 v55, v59
	v_mov_b32_e32 v53, v58
	v_pk_mul_f32 v[66:67], v[54:55], v[54:55]
	v_pk_mul_f32 v[58:59], v[52:53], v[52:53]
	v_fmac_f32_e32 v60, 0xba800000, v62
	v_pk_mov_b32 v[84:85], v[58:59], v[66:67] op_sel:[1,0]
	v_mov_b32_e32 v59, v67
	v_fmac_f32_e32 v61, 0xba800000, v62
	v_fmac_f32_e32 v65, 0xba800000, v62
	v_pk_add_f32 v[58:59], v[84:85], v[58:59]
	v_fmac_f32_e32 v64, 0xba800000, v62
	v_mov_b32_e32 v66, v65
	v_mov_b32_e32 v67, v61
	v_mov_b32_e32 v65, v60
	v_pk_add_f32 v[58:59], v[58:59], v[58:59] op_sel_hi:[0,1]
	v_pk_mul_f32 v[84:85], v[66:67], v[66:67]
	v_pk_mul_f32 v[60:61], v[64:65], v[64:65]
	v_fmac_f32_e32 v68, 0xba800000, v62
	v_pk_mov_b32 v[86:87], v[60:61], v[84:85] op_sel:[1,0]
	v_mov_b32_e32 v61, v85
	v_fmac_f32_e32 v69, 0xba800000, v62
	v_fmac_f32_e32 v56, 0xba800000, v62
	v_mul_f32_e32 v58, v68, v68
	v_pk_add_f32 v[60:61], v[86:87], v[60:61]
	v_fmac_f32_e32 v57, 0xba800000, v62
	v_pk_fma_f32 v[84:85], v[68:69], v[68:69], v[58:59] op_sel_hi:[1,1,0]
	v_mul_f32_e32 v58, v56, v56
	v_pk_add_f32 v[60:61], v[60:61], v[60:61] op_sel_hi:[0,1]
	v_pk_fma_f32 v[86:87], v[56:57], v[56:57], v[58:59] op_sel_hi:[1,1,0]
	v_fmac_f32_e32 v73, 0xba800000, v62
	v_fmac_f32_e32 v71, 0xba800000, v62
	v_fmac_f32_e32 v83, 0xba800000, v62
	v_fmac_f32_e32 v63, 0xba800000, v62
	v_mul_f32_e32 v84, v63, v63
	v_mul_f32_e32 v86, v83, v83
	v_mul_f32_e32 v58, v71, v71
	v_mul_f32_e32 v60, v73, v73
	v_pk_add_f32 v[84:85], v[84:85], v[86:87]
	v_pk_add_f32 v[58:59], v[58:59], v[60:61]
	s_nop 0
	v_pk_add_f32 v[58:59], v[84:85], v[58:59]
	s_nop 0
	v_add_f32_e32 v58, v58, v59
	ds_bpermute_b32 v59, v74, v58
	s_waitcnt lgkmcnt(0)
	v_add_f32_e32 v58, v58, v59
	ds_bpermute_b32 v59, v75, v58
	s_waitcnt lgkmcnt(0)
	v_add_f32_e32 v58, v58, v59
	ds_bpermute_b32 v59, v76, v58
	s_waitcnt lgkmcnt(0)
	v_add_f32_e32 v58, v58, v59
	ds_bpermute_b32 v59, v77, v58
	s_waitcnt lgkmcnt(0)
	v_add_f32_e32 v58, v58, v59
	ds_bpermute_b32 v59, v78, v58
	s_waitcnt lgkmcnt(0)
	v_add_f32_e32 v58, v58, v59
	ds_bpermute_b32 v59, v79, v58
	s_waitcnt lgkmcnt(0)
	v_add_f32_e32 v58, v58, v59
	v_fmamk_f32 v58, v58, 0x3a800000, v80
	v_mul_f32_e32 v59, 0x4f800000, v58
	v_cmp_gt_f32_e32 vcc, s20, v58
	s_nop 1
	v_cndmask_b32_e32 v58, v58, v59, vcc
	v_sqrt_f32_e32 v59, v58
	s_nop 0
	v_add_u32_e32 v60, -1, v59
	v_fma_f32 v61, -v60, v59, v58
	v_cmp_ge_f32_e64 s[0:1], 0, v61
	v_add_u32_e32 v61, 1, v59
	s_nop 0
	v_cndmask_b32_e64 v60, v59, v60, s[0:1]
	v_fma_f32 v59, -v61, v59, v58
	v_cmp_lt_f32_e64 s[0:1], 0, v59
	s_nop 1
	v_cndmask_b32_e64 v59, v60, v61, s[0:1]
	v_mul_f32_e32 v60, 0x37800000, v59
	v_cndmask_b32_e32 v59, v59, v60, vcc
	v_cmp_class_f32_e32 vcc, v58, v81
	s_nop 1
	v_cndmask_b32_e32 v60, v59, v58, vcc
	v_div_scale_f32 v61, s[0:1], v60, v60, 1.0
	v_rcp_f32_e32 v62, v61
	s_lshl_b64 s[0:1], s[2:3], 12
	v_lshl_add_u64 v[58:59], v[34:35], 0, s[0:1]
	v_fma_f32 v70, -v61, v62, 1.0
	v_fmac_f32_e32 v62, v70, v62
	v_div_scale_f32 v70, vcc, 1.0, v60, 1.0
	v_mul_f32_e32 v72, v70, v62
	v_fma_f32 v82, -v61, v72, v70
	v_fmac_f32_e32 v72, v82, v62
	v_fma_f32 v61, -v61, v72, v70
	v_div_fmas_f32 v61, v61, v62, v72
	v_div_fixup_f32 v60, v61, v60, 1.0
	v_pk_mul_f32 v[52:53], v[52:53], v[60:61] op_sel_hi:[1,0]
	v_pk_mul_f32 v[54:55], v[54:55], v[60:61] op_sel_hi:[1,0]
	v_pk_fma_f32 v[52:53], v[0:1], v[52:53], v[4:5]
	v_pk_fma_f32 v[54:55], v[2:3], v[54:55], v[6:7]
	global_store_dwordx4 v[58:59], v[52:55], off sc1
	v_mov_b32_e32 v82, v63
	v_mov_b32_e32 v72, v71
	v_pk_mul_f32 v[52:53], v[64:65], v[60:61] op_sel_hi:[1,0]
	v_pk_mul_f32 v[54:55], v[66:67], v[60:61] op_sel_hi:[1,0]
	v_pk_fma_f32 v[52:53], v[8:9], v[52:53], v[16:17]
	v_pk_fma_f32 v[54:55], v[10:11], v[54:55], v[18:19]
	global_store_dwordx4 v[58:59], v[52:55], off offset:1024 sc1
	s_nop 1
	v_pk_mul_f32 v[52:53], v[68:69], v[60:61] op_sel_hi:[1,0]
	v_pk_mul_f32 v[54:55], v[56:57], v[60:61] op_sel_hi:[1,0]
	v_pk_fma_f32 v[52:53], v[12:13], v[52:53], v[20:21]
	v_pk_fma_f32 v[54:55], v[14:15], v[54:55], v[22:23]
	global_store_dwordx4 v[58:59], v[52:55], off offset:2048 sc1
	s_nop 1
	v_pk_mul_f32 v[52:53], v[82:83], v[60:61] op_sel_hi:[1,0]
	v_pk_mul_f32 v[54:55], v[72:73], v[60:61] op_sel_hi:[1,0]
	v_pk_fma_f32 v[52:53], v[24:25], v[52:53], v[28:29]
	v_pk_fma_f32 v[54:55], v[26:27], v[54:55], v[30:31]
	global_store_dwordx4 v[58:59], v[52:55], off offset:3072 sc1
	s_andn2_b64 vcc, exec, s[10:11]
	s_cbranch_vccz .LBB0_1113

.LBB0_1113:
	s_waitcnt vmcnt(11)
	v_lshlrev_b32_e32 v53, 16, v51
	v_lshlrev_b32_e32 v52, 16, v50
	v_and_b32_e32 v51, 0xffff0000, v51
	v_and_b32_e32 v50, 0xffff0000, v50
	s_waitcnt vmcnt(10)
	v_lshlrev_b32_e32 v57, 16, v49
	v_lshlrev_b32_e32 v56, 16, v48
	v_and_b32_e32 v49, 0xffff0000, v49
	v_and_b32_e32 v48, 0xffff0000, v48
	v_pk_add_f32 v[54:55], v[52:53], v[50:51]
	v_pk_add_f32 v[58:59], v[56:57], v[48:49]
	v_add_f32_e32 v54, v54, v55
	s_waitcnt vmcnt(9)
	v_lshlrev_b32_e32 v60, 16, v46
	v_and_b32_e32 v61, 0xffff0000, v46
	v_lshlrev_b32_e32 v62, 16, v47
	v_and_b32_e32 v63, 0xffff0000, v47
	s_waitcnt vmcnt(8)
	v_lshlrev_b32_e32 v55, 16, v44
	v_and_b32_e32 v69, 0xffff0000, v44
	v_lshlrev_b32_e32 v65, 16, v45
	v_and_b32_e32 v67, 0xffff0000, v45
	v_pk_add_f32 v[44:45], v[58:59], v[58:59] op_sel:[0,1] op_sel_hi:[1,0]
	v_add_f32_e32 v54, 0, v54
	v_add_f32_e32 v64, v60, v61
	v_add_f32_e32 v66, v62, v63
	v_mov_b32_e32 v45, v69
	v_pk_add_f32 v[44:45], v[54:55], v[44:45]
	v_pk_add_f32 v[46:47], v[64:65], v[66:67]
	s_ashr_i32 s9, s8, 31
	v_pk_add_f32 v[44:45], v[44:45], v[46:47]
	s_nop 0
	v_add_f32_e32 v44, v44, v45
	ds_bpermute_b32 v45, v74, v44
	s_waitcnt lgkmcnt(0)
	v_add_f32_e32 v44, v44, v45
	ds_bpermute_b32 v45, v75, v44
	s_waitcnt lgkmcnt(0)
	v_add_f32_e32 v44, v44, v45
	ds_bpermute_b32 v45, v76, v44
	s_waitcnt lgkmcnt(0)
	v_add_f32_e32 v44, v44, v45
	ds_bpermute_b32 v45, v77, v44
	s_waitcnt lgkmcnt(0)
	v_add_f32_e32 v44, v44, v45
	ds_bpermute_b32 v45, v78, v44
	s_waitcnt lgkmcnt(0)
	v_add_f32_e32 v44, v44, v45
	ds_bpermute_b32 v45, v79, v44
	s_waitcnt lgkmcnt(0)
	v_add_f32_e32 v54, v44, v45
	v_fmac_f32_e32 v50, 0xba800000, v54
	v_fmac_f32_e32 v51, 0xba800000, v54
	v_fmac_f32_e32 v53, 0xba800000, v54
	v_fmac_f32_e32 v52, 0xba800000, v54
	v_mov_b32_e32 v44, v53
	v_mov_b32_e32 v45, v51
	v_mov_b32_e32 v53, v50
	v_pk_mul_f32 v[46:47], v[44:45], v[44:45]
	v_pk_mul_f32 v[50:51], v[52:53], v[52:53]
	v_fmac_f32_e32 v48, 0xba800000, v54
	v_pk_mov_b32 v[58:59], v[50:51], v[46:47] op_sel:[1,0]
	v_mov_b32_e32 v51, v47
	v_fmac_f32_e32 v49, 0xba800000, v54
	v_fmac_f32_e32 v57, 0xba800000, v54
	v_pk_add_f32 v[46:47], v[58:59], v[50:51]
	v_fmac_f32_e32 v56, 0xba800000, v54
	v_mov_b32_e32 v50, v57
	v_mov_b32_e32 v51, v49
	v_mov_b32_e32 v57, v48
	v_pk_add_f32 v[46:47], v[46:47], v[46:47] op_sel_hi:[0,1]
	v_pk_mul_f32 v[58:59], v[50:51], v[50:51]
	v_pk_mul_f32 v[48:49], v[56:57], v[56:57]
	v_fmac_f32_e32 v60, 0xba800000, v54
	v_pk_mov_b32 v[70:71], v[48:49], v[58:59] op_sel:[1,0]
	v_mov_b32_e32 v49, v59
	v_fmac_f32_e32 v61, 0xba800000, v54
	v_fmac_f32_e32 v62, 0xba800000, v54
	v_mul_f32_e32 v46, v60, v60
	v_pk_add_f32 v[48:49], v[70:71], v[48:49]
	v_fmac_f32_e32 v63, 0xba800000, v54
	v_pk_fma_f32 v[58:59], v[60:61], v[60:61], v[46:47] op_sel_hi:[1,1,0]
	v_mul_f32_e32 v46, v62, v62
	v_pk_add_f32 v[48:49], v[48:49], v[48:49] op_sel_hi:[0,1]
	v_pk_fma_f32 v[70:71], v[62:63], v[62:63], v[46:47] op_sel_hi:[1,1,0]
	v_fmac_f32_e32 v67, 0xba800000, v54
	v_fmac_f32_e32 v65, 0xba800000, v54
	v_fmac_f32_e32 v69, 0xba800000, v54
	v_fmac_f32_e32 v55, 0xba800000, v54
	v_mul_f32_e32 v58, v55, v55
	v_mul_f32_e32 v70, v69, v69
	v_mul_f32_e32 v46, v65, v65
	v_mul_f32_e32 v48, v67, v67
	v_pk_add_f32 v[58:59], v[58:59], v[70:71]
	v_pk_add_f32 v[46:47], v[46:47], v[48:49]
	v_mov_b32_e32 v68, v55
	v_pk_add_f32 v[46:47], v[58:59], v[46:47]
	v_mov_b32_e32 v66, v65
	v_add_f32_e32 v46, v46, v47
	ds_bpermute_b32 v47, v74, v46
	s_waitcnt lgkmcnt(0)
	v_add_f32_e32 v46, v46, v47
	ds_bpermute_b32 v47, v75, v46
	s_waitcnt lgkmcnt(0)
	v_add_f32_e32 v46, v46, v47
	ds_bpermute_b32 v47, v76, v46
	s_waitcnt lgkmcnt(0)
	v_add_f32_e32 v46, v46, v47
	ds_bpermute_b32 v47, v77, v46
	s_waitcnt lgkmcnt(0)
	v_add_f32_e32 v46, v46, v47
	ds_bpermute_b32 v47, v78, v46
	s_waitcnt lgkmcnt(0)
	v_add_f32_e32 v46, v46, v47
	ds_bpermute_b32 v47, v79, v46
	s_waitcnt lgkmcnt(0)
	v_add_f32_e32 v46, v46, v47
	v_fmamk_f32 v46, v46, 0x3a800000, v80
	v_mul_f32_e32 v47, 0x4f800000, v46
	v_cmp_gt_f32_e32 vcc, s20, v46
	s_nop 1
	v_cndmask_b32_e32 v46, v46, v47, vcc
	v_sqrt_f32_e32 v47, v46
	s_nop 0
	v_add_u32_e32 v48, -1, v47
	v_fma_f32 v49, -v48, v47, v46
	v_cmp_ge_f32_e64 s[0:1], 0, v49
	v_add_u32_e32 v49, 1, v47
	s_nop 0
	v_cndmask_b32_e64 v48, v47, v48, s[0:1]
	v_fma_f32 v47, -v49, v47, v46
	v_cmp_lt_f32_e64 s[0:1], 0, v47
	s_nop 1
	v_cndmask_b32_e64 v47, v48, v49, s[0:1]
	v_mul_f32_e32 v48, 0x37800000, v47
	v_cndmask_b32_e32 v47, v47, v48, vcc
	v_cmp_class_f32_e32 vcc, v46, v81
	s_nop 1
	v_cndmask_b32_e32 v46, v47, v46, vcc
	v_div_scale_f32 v47, s[0:1], v46, v46, 1.0
	v_rcp_f32_e32 v54, v47
	s_lshl_b64 s[0:1], s[8:9], 12
	v_lshl_add_u64 v[48:49], v[34:35], 0, s[0:1]
	v_fma_f32 v58, -v47, v54, 1.0
	v_fmac_f32_e32 v54, v58, v54
	v_div_scale_f32 v58, vcc, 1.0, v46, 1.0
	v_mul_f32_e32 v59, v58, v54
	v_fma_f32 v64, -v47, v59, v58
	v_fmac_f32_e32 v59, v64, v54
	v_fma_f32 v47, -v47, v59, v58
	v_div_fmas_f32 v47, v47, v54, v59
	v_div_fixup_f32 v54, v47, v46, 1.0
	v_pk_mul_f32 v[52:53], v[52:53], v[54:55] op_sel_hi:[1,0]
	v_pk_mul_f32 v[44:45], v[44:45], v[54:55] op_sel_hi:[1,0]
	s_nop 0
	v_pk_fma_f32 v[46:47], v[2:3], v[44:45], v[6:7]
	v_pk_fma_f32 v[44:45], v[0:1], v[52:53], v[4:5]
	global_store_dwordx4 v[48:49], v[44:47], off sc1
	s_nop 1
	v_pk_mul_f32 v[44:45], v[56:57], v[54:55] op_sel_hi:[1,0]
	v_pk_mul_f32 v[46:47], v[50:51], v[54:55] op_sel_hi:[1,0]
	v_pk_fma_f32 v[44:45], v[8:9], v[44:45], v[16:17]
	v_pk_fma_f32 v[46:47], v[10:11], v[46:47], v[18:19]
	global_store_dwordx4 v[48:49], v[44:47], off offset:1024 sc1
	s_nop 1
	v_pk_mul_f32 v[44:45], v[60:61], v[54:55] op_sel_hi:[1,0]
	v_pk_mul_f32 v[46:47], v[62:63], v[54:55] op_sel_hi:[1,0]
	v_pk_fma_f32 v[44:45], v[12:13], v[44:45], v[20:21]
	v_pk_fma_f32 v[46:47], v[14:15], v[46:47], v[22:23]
	global_store_dwordx4 v[48:49], v[44:47], off offset:2048 sc1
	s_nop 1
	v_pk_mul_f32 v[44:45], v[68:69], v[54:55] op_sel_hi:[1,0]
	v_pk_mul_f32 v[46:47], v[66:67], v[54:55] op_sel_hi:[1,0]
	v_pk_fma_f32 v[44:45], v[24:25], v[44:45], v[28:29]
	v_pk_fma_f32 v[46:47], v[26:27], v[46:47], v[30:31]
	global_store_dwordx4 v[48:49], v[44:47], off offset:3072 sc1
	s_andn2_b64 vcc, exec, s[6:7]
	s_cbranch_vccnz .LBB0_1108
.LBB0_1114:
	s_waitcnt vmcnt(7)
	v_lshlrev_b32_e32 v45, 16, v43
	v_lshlrev_b32_e32 v44, 16, v42
	v_and_b32_e32 v43, 0xffff0000, v43
	v_and_b32_e32 v42, 0xffff0000, v42
	s_waitcnt vmcnt(6)
	v_lshlrev_b32_e32 v49, 16, v41
	v_lshlrev_b32_e32 v48, 16, v40
	v_and_b32_e32 v41, 0xffff0000, v41
	v_and_b32_e32 v40, 0xffff0000, v40
	v_pk_add_f32 v[46:47], v[44:45], v[42:43]
	v_pk_add_f32 v[50:51], v[48:49], v[40:41]
	v_add_f32_e32 v46, v46, v47
	s_waitcnt vmcnt(5)
	v_lshlrev_b32_e32 v52, 16, v38
	v_and_b32_e32 v53, 0xffff0000, v38
	v_lshlrev_b32_e32 v54, 16, v39
	v_and_b32_e32 v55, 0xffff0000, v39
	s_waitcnt vmcnt(4)
	v_lshlrev_b32_e32 v47, 16, v36
	v_and_b32_e32 v61, 0xffff0000, v36
	v_lshlrev_b32_e32 v57, 16, v37
	v_and_b32_e32 v59, 0xffff0000, v37
	v_pk_add_f32 v[36:37], v[50:51], v[50:51] op_sel:[0,1] op_sel_hi:[1,0]
	v_add_f32_e32 v46, 0, v46
	v_add_f32_e32 v56, v52, v53
	v_add_f32_e32 v58, v54, v55
	v_mov_b32_e32 v37, v61
	v_pk_add_f32 v[36:37], v[46:47], v[36:37]
	v_pk_add_f32 v[38:39], v[56:57], v[58:59]
	s_ashr_i32 s5, s4, 31
	v_pk_add_f32 v[36:37], v[36:37], v[38:39]
	s_nop 0
	v_add_f32_e32 v36, v36, v37
	ds_bpermute_b32 v37, v74, v36
	s_waitcnt lgkmcnt(0)
	v_add_f32_e32 v36, v36, v37
	ds_bpermute_b32 v37, v75, v36
	s_waitcnt lgkmcnt(0)
	v_add_f32_e32 v36, v36, v37
	ds_bpermute_b32 v37, v76, v36
	s_waitcnt lgkmcnt(0)
	v_add_f32_e32 v36, v36, v37
	ds_bpermute_b32 v37, v77, v36
	s_waitcnt lgkmcnt(0)
	v_add_f32_e32 v36, v36, v37
	ds_bpermute_b32 v37, v78, v36
	s_waitcnt lgkmcnt(0)
	v_add_f32_e32 v36, v36, v37
	ds_bpermute_b32 v37, v79, v36
	s_waitcnt lgkmcnt(0)
	v_add_f32_e32 v46, v36, v37
	v_fmac_f32_e32 v42, 0xba800000, v46
	v_fmac_f32_e32 v43, 0xba800000, v46
	v_fmac_f32_e32 v45, 0xba800000, v46
	v_fmac_f32_e32 v44, 0xba800000, v46
	v_mov_b32_e32 v36, v45
	v_mov_b32_e32 v37, v43
	v_mov_b32_e32 v45, v42
	v_pk_mul_f32 v[38:39], v[36:37], v[36:37]
	v_pk_mul_f32 v[42:43], v[44:45], v[44:45]
	v_fmac_f32_e32 v40, 0xba800000, v46
	v_pk_mov_b32 v[50:51], v[42:43], v[38:39] op_sel:[1,0]
	v_mov_b32_e32 v43, v39
	v_fmac_f32_e32 v41, 0xba800000, v46
	v_fmac_f32_e32 v49, 0xba800000, v46
	v_pk_add_f32 v[38:39], v[50:51], v[42:43]
	v_fmac_f32_e32 v48, 0xba800000, v46
	v_mov_b32_e32 v42, v49
	v_mov_b32_e32 v43, v41
	v_mov_b32_e32 v49, v40
	v_pk_add_f32 v[38:39], v[38:39], v[38:39] op_sel_hi:[0,1]
	v_pk_mul_f32 v[50:51], v[42:43], v[42:43]
	v_pk_mul_f32 v[40:41], v[48:49], v[48:49]
	v_fmac_f32_e32 v52, 0xba800000, v46
	v_pk_mov_b32 v[62:63], v[40:41], v[50:51] op_sel:[1,0]
	v_mov_b32_e32 v41, v51
	v_fmac_f32_e32 v53, 0xba800000, v46
	v_fmac_f32_e32 v54, 0xba800000, v46
	v_mul_f32_e32 v38, v52, v52
	v_pk_add_f32 v[40:41], v[62:63], v[40:41]
	v_fmac_f32_e32 v55, 0xba800000, v46
	v_pk_fma_f32 v[50:51], v[52:53], v[52:53], v[38:39] op_sel_hi:[1,1,0]
	v_mul_f32_e32 v38, v54, v54
	v_pk_add_f32 v[40:41], v[40:41], v[40:41] op_sel_hi:[0,1]
	v_pk_fma_f32 v[62:63], v[54:55], v[54:55], v[38:39] op_sel_hi:[1,1,0]
	v_fmac_f32_e32 v59, 0xba800000, v46
	v_fmac_f32_e32 v57, 0xba800000, v46
	v_fmac_f32_e32 v61, 0xba800000, v46
	v_fmac_f32_e32 v47, 0xba800000, v46
	v_mul_f32_e32 v50, v47, v47
	v_mul_f32_e32 v62, v61, v61
	v_mul_f32_e32 v38, v57, v57
	v_mul_f32_e32 v40, v59, v59
	v_pk_add_f32 v[50:51], v[50:51], v[62:63]
	v_pk_add_f32 v[38:39], v[38:39], v[40:41]
	v_mov_b32_e32 v60, v47
	v_pk_add_f32 v[38:39], v[50:51], v[38:39]
	v_mov_b32_e32 v58, v57
	v_add_f32_e32 v38, v38, v39
	ds_bpermute_b32 v39, v74, v38
	s_waitcnt lgkmcnt(0)
	v_add_f32_e32 v38, v38, v39
	ds_bpermute_b32 v39, v75, v38
	s_waitcnt lgkmcnt(0)
	v_add_f32_e32 v38, v38, v39
	ds_bpermute_b32 v39, v76, v38
	s_waitcnt lgkmcnt(0)
	v_add_f32_e32 v38, v38, v39
	ds_bpermute_b32 v39, v77, v38
	s_waitcnt lgkmcnt(0)
	v_add_f32_e32 v38, v38, v39
	ds_bpermute_b32 v39, v78, v38
	s_waitcnt lgkmcnt(0)
	v_add_f32_e32 v38, v38, v39
	ds_bpermute_b32 v39, v79, v38
	s_waitcnt lgkmcnt(0)
	v_add_f32_e32 v38, v38, v39
	v_fmamk_f32 v38, v38, 0x3a800000, v80
	v_mul_f32_e32 v39, 0x4f800000, v38
	v_cmp_gt_f32_e32 vcc, s20, v38
	s_nop 1
	v_cndmask_b32_e32 v38, v38, v39, vcc
	v_sqrt_f32_e32 v39, v38
	s_nop 0
	v_add_u32_e32 v40, -1, v39
	v_fma_f32 v41, -v40, v39, v38
	v_cmp_ge_f32_e64 s[0:1], 0, v41
	v_add_u32_e32 v41, 1, v39
	s_nop 0
	v_cndmask_b32_e64 v40, v39, v40, s[0:1]
	v_fma_f32 v39, -v41, v39, v38
	v_cmp_lt_f32_e64 s[0:1], 0, v39
	s_nop 1
	v_cndmask_b32_e64 v39, v40, v41, s[0:1]
	v_mul_f32_e32 v40, 0x37800000, v39
	v_cndmask_b32_e32 v39, v39, v40, vcc
	v_cmp_class_f32_e32 vcc, v38, v81
	s_nop 1
	v_cndmask_b32_e32 v38, v39, v38, vcc
	v_div_scale_f32 v39, s[0:1], v38, v38, 1.0
	v_rcp_f32_e32 v46, v39
	s_lshl_b64 s[0:1], s[4:5], 12
	v_lshl_add_u64 v[40:41], v[34:35], 0, s[0:1]
	v_fma_f32 v50, -v39, v46, 1.0
	v_fmac_f32_e32 v46, v50, v46
	v_div_scale_f32 v50, vcc, 1.0, v38, 1.0
	v_mul_f32_e32 v51, v50, v46
	v_fma_f32 v56, -v39, v51, v50
	v_fmac_f32_e32 v51, v56, v46
	v_fma_f32 v39, -v39, v51, v50
	v_div_fmas_f32 v39, v39, v46, v51
	v_div_fixup_f32 v46, v39, v38, 1.0
	v_pk_mul_f32 v[44:45], v[44:45], v[46:47] op_sel_hi:[1,0]
	v_pk_mul_f32 v[36:37], v[36:37], v[46:47] op_sel_hi:[1,0]
	s_nop 0
	v_pk_fma_f32 v[38:39], v[2:3], v[36:37], v[6:7]
	v_pk_fma_f32 v[36:37], v[0:1], v[44:45], v[4:5]
	global_store_dwordx4 v[40:41], v[36:39], off sc1
	s_nop 1
	v_pk_mul_f32 v[36:37], v[48:49], v[46:47] op_sel_hi:[1,0]
	v_pk_mul_f32 v[38:39], v[42:43], v[46:47] op_sel_hi:[1,0]
	v_pk_fma_f32 v[36:37], v[8:9], v[36:37], v[16:17]
	v_pk_fma_f32 v[38:39], v[10:11], v[38:39], v[18:19]
	global_store_dwordx4 v[40:41], v[36:39], off offset:1024 sc1
	s_nop 1
	v_pk_mul_f32 v[36:37], v[52:53], v[46:47] op_sel_hi:[1,0]
	v_pk_mul_f32 v[38:39], v[54:55], v[46:47] op_sel_hi:[1,0]
	v_pk_fma_f32 v[36:37], v[12:13], v[36:37], v[20:21]
	v_pk_fma_f32 v[38:39], v[14:15], v[38:39], v[22:23]
	global_store_dwordx4 v[40:41], v[36:39], off offset:2048 sc1
	s_nop 1
	v_pk_mul_f32 v[36:37], v[60:61], v[46:47] op_sel_hi:[1,0]
	v_pk_mul_f32 v[38:39], v[58:59], v[46:47] op_sel_hi:[1,0]
	v_pk_fma_f32 v[36:37], v[24:25], v[36:37], v[28:29]
	v_pk_fma_f32 v[38:39], v[26:27], v[38:39], v[30:31]
	global_store_dwordx4 v[40:41], v[36:39], off offset:3072 sc1
	s_branch .LBB0_1108
